# baseline (speedup 1.0000x reference)
; #define LDS_BAR() do { asm volatile("s_waitcnt lgkmcnt(0)" ::: "memory"); __builtin_amdgcn_s_barrier(); } while (0)
; __device__ __forceinline__ void convert_weight(const float* __restrict__ src, bf16_t* __restrict__ dst, int K, int N,
;                                                const float* __restrict__ gain) {
;     ...
;       u32x2 w0 = {pk2(v[0][hh].x * g[0], v[1][hh].x * g[1]), pk2(v[2][hh].x * g[2], v[3][hh].x * g[3])};
;       u32x2 w1 = {pk2(v[0][hh].y * g[0], v[1][hh].y * g[1]), pk2(v[2][hh].y * g[2], v[3][hh].y * g[3])};
;       u32x2 w2 = {pk2(v[0][hh].z * g[0], v[1][hh].z * g[1]), pk2(v[2][hh].z * g[2], v[3][hh].z * g[3])};
;       u32x2 w3 = {pk2(v[0][hh].w * g[0], v[1][hh].w * g[1]), pk2(v[2][hh].w * g[2], v[3][hh].w * g[3])};
;       *(u32x2*)(lds + (64 * hh + 4 * nq + 0) * 136 + 4 * kq) = w0;
;       *(u32x2*)(lds + (64 * hh + 4 * nq + 1) * 136 + 4 * kq) = w1;
;       *(u32x2*)(lds + (64 * hh + 4 * nq + 2) * 136 + 4 * kq) = w2;
;       *(u32x2*)(lds + (64 * hh + 4 * nq + 3) * 136 + 4 * kq) = w3;
;     }
;     const int t2 = t + gridDim.x;
;     if (t2 < ntile) {
;       const int k2 = (t2 / tn) << 7, n2 = (t2 % tn) << 7;
; #pragma unroll
;       for (int i = 0; i < 4; ++i) {
;         const float* rp = src + (size_t)(k2 + 4 * kq + i) * N + n2 + 4 * nq;
;         v[i][0] = *(const float4*)rp; v[i][1] = *(const float4*)(rp + 64);
;         g[i] = gain ? gain[k2 + 4 * kq + i] : 1.0f;
;       }
;     }
;     LDS_BAR();
;     u32x4 o[4];
; #pragma unroll
;     for (int r = 0; r < 4; ++r) o[r] = *(const u32x4*)(lds + (32 * r + (tid >> 4)) * 136 + (tid & 15) * 8);
; #pragma unroll
;     for (int r = 0; r < 4; ++r) *(u32x4*)(dst + (size_t)(n0 + 32 * r + (tid >> 4)) * K + k0 + (tid & 15) * 8) = o[r];
;     LDS_BAR();
.LBB0_61:
	ds_write2_b64 v32, v[238:239], v[240:241] offset1:34
	ds_write2_b64 v32, v[242:243], v[244:245] offset0:68 offset1:102
	ds_write2_b64 v254, v[246:247], v[248:249] offset0:128 offset1:162
	ds_write2_b64 v254, v[250:251], v[252:253] offset0:196 offset1:230
	s_ashr_i32 s28, s26, 31
	s_abs_i32 s26, s26
	s_mul_hi_u32 s29, s26, s25
	s_mul_i32 s30, s29, s23
	s_sub_i32 s26, s26, s30
	s_add_i32 s30, s29, 1
	s_sub_i32 s31, s26, s23
	s_cmp_ge_u32 s26, s23
	s_cselect_b32 s29, s30, s29
	s_cselect_b32 s26, s31, s26
	s_add_i32 s30, s29, 1
	s_cmp_ge_u32 s26, s23
	s_cselect_b32 s26, s30, s29
	s_xor_b32 s26, s26, s28
	s_sub_i32 s26, s26, s28
	s_lshl_b32 s28, s26, 7
	s_mul_i32 s26, s12, s26
	s_add_i32 s26, s26, s19
	v_add_u32_e32 v47, s26, v44
	s_ashr_i32 s29, s28, 31
	v_lshl_add_u64 v[42:43], s[28:29], 1, v[40:41]
	v_mad_u64_u32 v[64:65], s[28:29], v47, s0, 0
	v_ashrrev_i32_e32 v67, 31, v47
	v_mov_b32_e32 v66, v65
	v_mad_u64_u32 v[66:67], s[28:29], v67, s0, v[66:67]
	s_waitcnt lgkmcnt(0)
	s_barrier
	ds_read_b128 v[48:51], v46
	ds_read_b128 v[52:55], v46 offset:8704
	ds_read_b128 v[56:59], v46 offset:17408
	ds_read_b128 v[60:63], v46 offset:26112
	v_mov_b32_e32 v65, v66
	v_lshl_add_u64 v[64:65], v[64:65], 1, v[42:43]
	s_waitcnt lgkmcnt(3)
	global_store_dwordx4 v[64:65], v[48:51], off
	v_add_u32_e32 v44, s13, v44
	s_add_i32 s15, s15, s13
	v_add_u32_e32 v48, 32, v47
	v_ashrrev_i32_e32 v51, 31, v48
	v_mad_u64_u32 v[48:49], s[28:29], v48, s0, 0
	v_mov_b32_e32 v50, v49
	v_mad_u64_u32 v[50:51], s[28:29], v51, s0, v[50:51]
	v_mov_b32_e32 v49, v50
	v_lshl_add_u64 v[48:49], v[48:49], 1, v[42:43]
	s_waitcnt lgkmcnt(2)
	global_store_dwordx4 v[48:49], v[52:55], off
	v_add_u32_e32 v48, 64, v47
	v_ashrrev_i32_e32 v51, 31, v48
	v_mad_u64_u32 v[48:49], s[28:29], v48, s0, 0
	v_mov_b32_e32 v50, v49
	v_mad_u64_u32 v[50:51], s[28:29], v51, s0, v[50:51]
	v_mov_b32_e32 v49, v50
	v_lshl_add_u64 v[48:49], v[48:49], 1, v[42:43]
	v_add_u32_e32 v47, 0x60, v47
	s_waitcnt lgkmcnt(1)
	global_store_dwordx4 v[48:49], v[56:59], off
	v_mad_u64_u32 v[48:49], s[28:29], v47, s0, 0
	v_ashrrev_i32_e32 v51, 31, v47
	v_mov_b32_e32 v50, v49
	v_mad_u64_u32 v[50:51], s[28:29], v51, s0, v[50:51]
	v_mov_b32_e32 v49, v50
	v_lshl_add_u64 v[42:43], v[48:49], 1, v[42:43]
	s_waitcnt lgkmcnt(0)
	global_store_dwordx4 v[42:43], v[60:63], off
	s_waitcnt lgkmcnt(0)
	s_andn2_b64 vcc, exec, s[10:11]
	s_mov_b32 s26, s27
	s_barrier
	s_cbranch_vccz .LBB0_33
.LBB0_62:
	s_waitcnt vmcnt(7)
	v_mov_b32_e32 v42, v0
	s_waitcnt vmcnt(5)
	v_mov_b32_e32 v43, v8
	s_waitcnt vmcnt(3)
	v_mov_b32_e32 v48, v16
	s_waitcnt vmcnt(1)
	v_mov_b32_e32 v49, v24
	v_pk_mul_f32 v[42:43], v[42:43], v[34:35]
	s_waitcnt vmcnt(0)
	v_pk_mul_f32 v[48:49], v[48:49], v[36:37]
	v_cvt_pk_bf16_f32 v238, v42, v43
	v_cvt_pk_bf16_f32 v239, v48, v49
	v_mov_b32_e32 v48, v1
	v_mov_b32_e32 v49, v9
	v_mov_b32_e32 v50, v17
	v_mov_b32_e32 v51, v25
	v_pk_mul_f32 v[48:49], v[48:49], v[34:35]
	v_pk_mul_f32 v[50:51], v[50:51], v[36:37]
	v_cvt_pk_bf16_f32 v240, v48, v49
	v_cvt_pk_bf16_f32 v241, v50, v51
	v_mov_b32_e32 v50, v2
	v_mov_b32_e32 v51, v10
	v_mov_b32_e32 v52, v18
	v_mov_b32_e32 v53, v26
	v_pk_mul_f32 v[50:51], v[50:51], v[34:35]
	v_pk_mul_f32 v[52:53], v[52:53], v[36:37]
	v_cvt_pk_bf16_f32 v242, v50, v51
	v_cvt_pk_bf16_f32 v243, v52, v53
	v_mov_b32_e32 v52, v3
	v_mov_b32_e32 v53, v11
	v_mov_b32_e32 v54, v19
	v_mov_b32_e32 v55, v27
	v_pk_mul_f32 v[52:53], v[52:53], v[34:35]
	v_pk_mul_f32 v[54:55], v[54:55], v[36:37]
	v_cvt_pk_bf16_f32 v244, v52, v53
	v_cvt_pk_bf16_f32 v245, v54, v55
	v_mov_b32_e32 v42, v4
	v_mov_b32_e32 v43, v12
	v_mov_b32_e32 v48, v20
	v_mov_b32_e32 v49, v28
	v_pk_mul_f32 v[42:43], v[42:43], v[34:35]
	v_pk_mul_f32 v[48:49], v[48:49], v[36:37]
	v_cvt_pk_bf16_f32 v246, v42, v43
	v_cvt_pk_bf16_f32 v247, v48, v49
	v_mov_b32_e32 v48, v5
	v_mov_b32_e32 v49, v13
	v_mov_b32_e32 v50, v21
	v_mov_b32_e32 v51, v29
	v_pk_mul_f32 v[48:49], v[48:49], v[34:35]
	v_pk_mul_f32 v[50:51], v[50:51], v[36:37]
	v_cvt_pk_bf16_f32 v248, v48, v49
	v_cvt_pk_bf16_f32 v249, v50, v51
	v_mov_b32_e32 v50, v6
	v_mov_b32_e32 v51, v14
	v_mov_b32_e32 v52, v22
	v_mov_b32_e32 v53, v30
	s_add_i32 s27, s14, s26
	v_pk_mul_f32 v[50:51], v[50:51], v[34:35]
	v_pk_mul_f32 v[52:53], v[52:53], v[36:37]
	s_cmp_ge_i32 s27, s24
	v_cvt_pk_bf16_f32 v250, v50, v51
	v_cvt_pk_bf16_f32 v251, v52, v53
	v_mov_b32_e32 v52, v7
	v_mov_b32_e32 v53, v15
	v_mov_b32_e32 v54, v23
	v_mov_b32_e32 v55, v31
	s_cselect_b64 s[10:11], -1, 0
	v_pk_mul_f32 v[52:53], v[52:53], v[34:35]
	v_pk_mul_f32 v[54:55], v[54:55], v[36:37]
	v_add_u32_e32 v254, 0x4000, v32
	s_and_b64 vcc, exec, s[10:11]
	v_cvt_pk_bf16_f32 v252, v52, v53
	v_cvt_pk_bf16_f32 v253, v54, v55
	s_cbranch_vccnz .LBB0_61
	s_abs_i32 s29, s27
	s_mul_hi_u32 s30, s29, s25
	s_mul_i32 s31, s30, s23
	s_sub_i32 s29, s29, s31
	s_ashr_i32 s28, s27, 31
	s_add_i32 s31, s30, 1
	s_sub_i32 s34, s29, s23
	s_cmp_ge_u32 s29, s23
	s_cselect_b32 s30, s31, s30
	s_cselect_b32 s29, s34, s29
	s_add_i32 s31, s30, 1
	s_cmp_ge_u32 s29, s23
	s_cselect_b32 s29, s31, s30
	s_xor_b32 s29, s29, s28
	s_sub_i32 s29, s29, s28
	s_mul_i32 s28, s12, s29
	s_add_i32 s30, s19, s15
	s_add_i32 s28, s30, s28
	v_lshl_add_u32 v26, s29, 7, v45
	s_ashr_i32 s29, s28, 31
	v_lshl_add_u64 v[24:25], s[28:29], 2, v[38:39]
	v_mad_u64_u32 v[0:1], s[28:29], v26, s22, 0
	v_ashrrev_i32_e32 v27, 31, v26
	v_mov_b32_e32 v2, v1
	v_mad_u64_u32 v[2:3], s[28:29], v27, s22, v[2:3]
	v_mov_b32_e32 v1, v2
	v_lshl_add_u64 v[4:5], v[0:1], 2, v[24:25]
	global_load_dwordx4 v[0:3], v[4:5], off
	s_nop 0
	global_load_dwordx4 v[4:7], v[4:5], off offset:256
	v_mov_b32_e32 v35, 1.0
	s_and_b64 vcc, exec, s[4:5]
	v_lshl_add_u64 v[42:43], v[26:27], 2, s[8:9]
	v_mov_b32_e32 v34, 1.0
	s_cbranch_vccnz .LBB0_65
	global_load_dword v34, v[42:43], off
